# saddr K-loop loads + MMA head trim + deferred pre_load wait in P3/P12 epilogues + v_mov_b64 accumulator zero-init
# speedup vs baseline: 1.0097x; 1.0097x over previous
.LBB0_169:
	s_cmp_eq_u32 s64, 0
	s_cselect_b32 s0, s59, 0x5cc00000
	s_cselect_b32 s21, s60, 0x2fb00000
	s_add_u32 s0, s4, s0
	s_addc_u32 s28, s5, 0
	s_ashr_i32 s23, s22, 31
	s_lshl_b64 s[26:27], s[22:23], 21
	s_add_u32 s26, s0, s26
	s_addc_u32 s27, s28, s27
	s_and_b64 s[28:29], s[24:25], exec
	s_cselect_b32 s23, s27, s43
	s_cselect_b32 s41, s26, s42
	s_add_u32 s0, s4, s21
	s_addc_u32 s52, s5, 0
	s_ashr_i32 s21, s20, 31
	s_lshl_b64 s[28:29], s[20:21], 21
	s_add_u32 s28, s0, s28
	s_addc_u32 s29, s52, s29
	s_and_b64 s[52:53], s[24:25], exec
	s_cselect_b32 s21, s29, s51
	s_cselect_b32 s66, s28, s50
	s_add_u32 s42, s42, 0x100080
	s_addc_u32 s43, s43, 0
	s_add_u32 s67, s50, 0x100
	v_mov_b32_e32 v8, 0
	s_addc_u32 s68, s51, 0
	s_mov_b32 s70, -2
	v_mov_b32_e32 v9, 0
	v_mov_b64_e32 v[10:11], 0
	v_mov_b64_e32 v[12:13], 0
	v_mov_b64_e32 v[14:15], 0
	v_mov_b64_e32 v[24:25], 0
	v_mov_b64_e32 v[26:27], 0
	v_mov_b64_e32 v[28:29], 0
	v_mov_b64_e32 v[30:31], 0
	v_mov_b64_e32 v[40:41], 0
	v_mov_b64_e32 v[42:43], 0
	v_mov_b64_e32 v[44:45], 0
	v_mov_b64_e32 v[46:47], 0
	v_mov_b64_e32 v[56:57], 0
	v_mov_b64_e32 v[58:59], 0
	v_mov_b64_e32 v[60:61], 0
	v_mov_b64_e32 v[62:63], 0
	v_mov_b64_e32 v[16:17], 0
	v_mov_b64_e32 v[18:19], 0
	v_mov_b64_e32 v[20:21], 0
	v_mov_b64_e32 v[22:23], 0
	v_mov_b64_e32 v[32:33], 0
	v_mov_b64_e32 v[34:35], 0
	v_mov_b64_e32 v[36:37], 0
	v_mov_b64_e32 v[38:39], 0
	v_mov_b64_e32 v[48:49], 0
	v_mov_b64_e32 v[50:51], 0
	v_mov_b64_e32 v[52:53], 0
	v_mov_b64_e32 v[54:55], 0
	v_mov_b64_e32 v[64:65], 0
	v_mov_b64_e32 v[66:67], 0
	v_mov_b64_e32 v[68:69], 0
	v_mov_b64_e32 v[70:71], 0
	v_mov_b64_e32 v[72:73], 0
	v_mov_b64_e32 v[74:75], 0
	v_mov_b64_e32 v[76:77], 0
	v_mov_b64_e32 v[78:79], 0
	v_mov_b64_e32 v[88:89], 0
	v_mov_b64_e32 v[90:91], 0
	v_mov_b64_e32 v[92:93], 0
	v_mov_b64_e32 v[94:95], 0
	v_mov_b64_e32 v[104:105], 0
	v_mov_b64_e32 v[106:107], 0
	v_mov_b64_e32 v[108:109], 0
	v_mov_b64_e32 v[110:111], 0
	v_mov_b64_e32 v[120:121], 0
	v_mov_b64_e32 v[122:123], 0
	v_mov_b64_e32 v[124:125], 0
	v_mov_b64_e32 v[126:127], 0
	v_mov_b64_e32 v[80:81], 0
	v_mov_b64_e32 v[82:83], 0
	v_mov_b64_e32 v[84:85], 0
	v_mov_b64_e32 v[86:87], 0
	v_mov_b64_e32 v[96:97], 0
	v_mov_b64_e32 v[98:99], 0
	v_mov_b64_e32 v[100:101], 0
	v_mov_b64_e32 v[102:103], 0
	v_mov_b64_e32 v[112:113], 0
	v_mov_b64_e32 v[114:115], 0
	v_mov_b64_e32 v[116:117], 0
	v_mov_b64_e32 v[118:119], 0
	v_mov_b64_e32 v[128:129], 0
	v_mov_b64_e32 v[130:131], 0
	v_mov_b64_e32 v[132:133], 0
	v_mov_b64_e32 v[134:135], 0

.LBB0_341:
	s_add_u32 s26, s26, 0x2b0080
	s_addc_u32 s27, s27, 0
	s_add_u32 s60, s28, 0x100
	v_mov_b32_e32 v4, 0
	s_addc_u32 s61, s29, 0
	s_mov_b32 s62, -2
	s_waitcnt lgkmcnt(0)
	v_mov_b32_e32 v5, 0
	v_mov_b64_e32 v[6:7], 0
	v_mov_b64_e32 v[8:9], 0
	v_mov_b64_e32 v[10:11], 0
	v_mov_b64_e32 v[20:21], 0
	v_mov_b64_e32 v[22:23], 0
	v_mov_b64_e32 v[24:25], 0
	v_mov_b64_e32 v[26:27], 0
	v_mov_b64_e32 v[36:37], 0
	v_mov_b64_e32 v[38:39], 0
	v_mov_b64_e32 v[40:41], 0
	v_mov_b64_e32 v[42:43], 0
	v_mov_b64_e32 v[52:53], 0
	v_mov_b64_e32 v[54:55], 0
	v_mov_b64_e32 v[56:57], 0
	v_mov_b64_e32 v[58:59], 0
	v_mov_b64_e32 v[12:13], 0
	v_mov_b64_e32 v[14:15], 0
	v_mov_b64_e32 v[16:17], 0
	v_mov_b64_e32 v[18:19], 0
	v_mov_b64_e32 v[28:29], 0
	v_mov_b64_e32 v[30:31], 0
	v_mov_b64_e32 v[32:33], 0
	v_mov_b64_e32 v[34:35], 0
	v_mov_b64_e32 v[44:45], 0
	v_mov_b64_e32 v[46:47], 0
	v_mov_b64_e32 v[48:49], 0
	v_mov_b64_e32 v[50:51], 0
	v_mov_b64_e32 v[60:61], 0
	v_mov_b64_e32 v[62:63], 0
	v_mov_b64_e32 v[64:65], 0
	v_mov_b64_e32 v[66:67], 0
	v_mov_b64_e32 v[68:69], 0
	v_mov_b64_e32 v[70:71], 0
	v_mov_b64_e32 v[72:73], 0
	v_mov_b64_e32 v[74:75], 0
	v_mov_b64_e32 v[84:85], 0
	v_mov_b64_e32 v[86:87], 0
	v_mov_b64_e32 v[88:89], 0
	v_mov_b64_e32 v[90:91], 0
	v_mov_b64_e32 v[100:101], 0
	v_mov_b64_e32 v[102:103], 0
	v_mov_b64_e32 v[104:105], 0
	v_mov_b64_e32 v[106:107], 0
	v_mov_b64_e32 v[116:117], 0
	v_mov_b64_e32 v[118:119], 0
	v_mov_b64_e32 v[120:121], 0
	v_mov_b64_e32 v[122:123], 0
	v_mov_b64_e32 v[76:77], 0
	v_mov_b64_e32 v[78:79], 0
	v_mov_b64_e32 v[80:81], 0
	v_mov_b64_e32 v[82:83], 0
	v_mov_b64_e32 v[92:93], 0
	v_mov_b64_e32 v[94:95], 0
	v_mov_b64_e32 v[96:97], 0
	v_mov_b64_e32 v[98:99], 0
	v_mov_b64_e32 v[108:109], 0
	v_mov_b64_e32 v[110:111], 0
	v_mov_b64_e32 v[112:113], 0
	v_mov_b64_e32 v[114:115], 0
	v_mov_b64_e32 v[124:125], 0
	v_mov_b64_e32 v[126:127], 0
	v_mov_b64_e32 v[128:129], 0
	v_mov_b64_e32 v[130:131], 0

.LBB0_428:
	s_ashr_i32 s27, s26, 31
	s_lshl_b64 s[28:29], s[26:27], 21
	s_add_u32 s28, s35, s28
	s_addc_u32 s29, s45, s29
	s_and_b64 s[30:31], exec, s[6:7]
	s_cselect_b32 s27, s51, s29
	s_cselect_b32 s67, s50, s28
	s_ashr_i32 s25, s24, 31
	s_lshl_b64 s[30:31], s[24:25], 21
	s_add_u32 s30, s46, s30
	s_addc_u32 s31, s47, s31
	s_and_b64 s[54:55], exec, s[6:7]
	s_cselect_b32 s25, s53, s31
	s_cselect_b32 s68, s52, s30
	s_add_u32 s50, s50, 0x100080
	s_addc_u32 s51, s51, 0
	s_add_u32 s70, s52, 0x100
	v_mov_b32_e32 v4, 0
	s_addc_u32 s71, s53, 0
	s_mov_b32 s72, -2
	v_mov_b32_e32 v5, 0
	v_mov_b64_e32 v[6:7], 0
	v_mov_b64_e32 v[8:9], 0
	v_mov_b64_e32 v[10:11], 0
	v_mov_b64_e32 v[20:21], 0
	v_mov_b64_e32 v[22:23], 0
	v_mov_b64_e32 v[24:25], 0
	v_mov_b64_e32 v[26:27], 0
	v_mov_b64_e32 v[36:37], 0
	v_mov_b64_e32 v[38:39], 0
	v_mov_b64_e32 v[40:41], 0
	v_mov_b64_e32 v[42:43], 0
	v_mov_b64_e32 v[52:53], 0
	v_mov_b64_e32 v[54:55], 0
	v_mov_b64_e32 v[56:57], 0
	v_mov_b64_e32 v[58:59], 0
	v_mov_b64_e32 v[12:13], 0
	v_mov_b64_e32 v[14:15], 0
	v_mov_b64_e32 v[16:17], 0
	v_mov_b64_e32 v[18:19], 0
	v_mov_b64_e32 v[28:29], 0
	v_mov_b64_e32 v[30:31], 0
	v_mov_b64_e32 v[32:33], 0
	v_mov_b64_e32 v[34:35], 0
	v_mov_b64_e32 v[44:45], 0
	v_mov_b64_e32 v[46:47], 0
	v_mov_b64_e32 v[48:49], 0
	v_mov_b64_e32 v[50:51], 0
	v_mov_b64_e32 v[60:61], 0
	v_mov_b64_e32 v[62:63], 0
	v_mov_b64_e32 v[64:65], 0
	v_mov_b64_e32 v[66:67], 0
	v_mov_b64_e32 v[68:69], 0
	v_mov_b64_e32 v[70:71], 0
	v_mov_b64_e32 v[72:73], 0
	v_mov_b64_e32 v[74:75], 0
	v_mov_b64_e32 v[84:85], 0
	v_mov_b64_e32 v[86:87], 0
	v_mov_b64_e32 v[88:89], 0
	v_mov_b64_e32 v[90:91], 0
	v_mov_b64_e32 v[100:101], 0
	v_mov_b64_e32 v[102:103], 0
	v_mov_b64_e32 v[104:105], 0
	v_mov_b64_e32 v[106:107], 0
	v_mov_b64_e32 v[116:117], 0
	v_mov_b64_e32 v[118:119], 0
	v_mov_b64_e32 v[120:121], 0
	v_mov_b64_e32 v[122:123], 0
	v_mov_b64_e32 v[76:77], 0
	v_mov_b64_e32 v[78:79], 0
	v_mov_b64_e32 v[80:81], 0
	v_mov_b64_e32 v[82:83], 0
	v_mov_b64_e32 v[92:93], 0
	v_mov_b64_e32 v[94:95], 0
	v_mov_b64_e32 v[96:97], 0
	v_mov_b64_e32 v[98:99], 0
	v_mov_b64_e32 v[108:109], 0
	v_mov_b64_e32 v[110:111], 0
	v_mov_b64_e32 v[112:113], 0
	v_mov_b64_e32 v[114:115], 0
	v_mov_b64_e32 v[124:125], 0
	v_mov_b64_e32 v[126:127], 0
	v_mov_b64_e32 v[128:129], 0
	v_mov_b64_e32 v[130:131], 0

.LBB0_432:
	s_nor_b64 s[50:51], s[2:3], s[6:7]
	v_mov_b32_e32 v161, 0x3a83126f
	s_and_saveexec_b64 s[52:53], s[50:51]
	s_cbranch_execz .LBB0_434
	v_lshl_or_b32 v224, s26, 8, v0
	v_ashrrev_i32_e32 v225, 31, v224
	v_lshl_add_u64 v[224:225], v[224:225], 3, s[12:13]
	global_load_dwordx2 v[222:223], v[224:225], off
.LBB0_434:
	s_or_b64 exec, exec, s[52:53]
	v_lshl_add_u32 v168, s57, 10, v154
	ds_read_b32 v162, v168
	v_lshl_or_b32 v152, s42, 8, v155
	v_lshl_add_u32 v163, s40, 8, v3
	v_ashrrev_i32_e32 v153, 31, v152
	v_mov_b64_e32 v[150:151], s[16:17]
	v_mad_i64_i32 v[164:165], s[6:7], v163, s65, v[150:151]
	v_lshlrev_b64 v[152:153], 1, v[152:153]
	v_lshl_add_u64 v[164:165], v[164:165], 0, v[152:153]
	s_waitcnt lgkmcnt(0)
	v_pk_mul_f32 v[130:131], v[130:131], v[162:163] op_sel_hi:[1,0]
	v_pk_mul_f32 v[128:129], v[128:129], v[162:163] op_sel_hi:[1,0]
	v_pk_mul_f32 v[166:167], v[126:127], v[162:163] op_sel_hi:[1,0]
	v_pk_mul_f32 v[126:127], v[124:125], v[162:163] op_sel_hi:[1,0]
	v_cvt_pk_bf16_f32 v124, v128, v129
	v_cvt_pk_bf16_f32 v125, v130, v131
	v_pk_mul_f32 v[120:121], v[120:121], v[162:163] op_sel_hi:[1,0]
	v_cvt_pk_bf16_f32 v126, v126, v127
	v_cvt_pk_bf16_f32 v127, v166, v167
	global_store_dwordx4 v[164:165], v[124:127], off
	v_pk_mul_f32 v[122:123], v[122:123], v[162:163] op_sel_hi:[1,0]
	s_nop 0
	v_pk_mul_f32 v[124:125], v[118:119], v[162:163] op_sel_hi:[1,0]
	v_pk_mul_f32 v[118:119], v[116:117], v[162:163] op_sel_hi:[1,0]
	v_cvt_pk_bf16_f32 v116, v120, v121
	v_cvt_pk_bf16_f32 v117, v122, v123
	s_nop 0
	v_cvt_pk_bf16_f32 v118, v118, v119
	v_cvt_pk_bf16_f32 v119, v124, v125
	global_store_dwordx4 v[164:165], v[116:119], off offset:256
	ds_read_b32 v116, v168 offset:64
	s_nop 0
	v_or_b32_e32 v117, 16, v163
	v_mad_i64_i32 v[118:119], s[6:7], v117, s65, v[150:151]
	v_lshl_add_u64 v[118:119], v[118:119], 0, v[152:153]
	s_waitcnt lgkmcnt(0)
	v_pk_mul_f32 v[114:115], v[114:115], v[116:117] op_sel_hi:[1,0]
	v_pk_mul_f32 v[112:113], v[112:113], v[116:117] op_sel_hi:[1,0]
	v_pk_mul_f32 v[120:121], v[110:111], v[116:117] op_sel_hi:[1,0]
	v_pk_mul_f32 v[110:111], v[108:109], v[116:117] op_sel_hi:[1,0]
	v_cvt_pk_bf16_f32 v108, v112, v113
	v_cvt_pk_bf16_f32 v109, v114, v115
	v_pk_mul_f32 v[104:105], v[104:105], v[116:117] op_sel_hi:[1,0]
	v_cvt_pk_bf16_f32 v110, v110, v111
	v_cvt_pk_bf16_f32 v111, v120, v121
	global_store_dwordx4 v[118:119], v[108:111], off
	v_pk_mul_f32 v[106:107], v[106:107], v[116:117] op_sel_hi:[1,0]
	s_nop 0
	v_pk_mul_f32 v[108:109], v[102:103], v[116:117] op_sel_hi:[1,0]
	v_pk_mul_f32 v[102:103], v[100:101], v[116:117] op_sel_hi:[1,0]
	v_cvt_pk_bf16_f32 v100, v104, v105
	v_cvt_pk_bf16_f32 v101, v106, v107
	s_nop 0
	v_cvt_pk_bf16_f32 v102, v102, v103
	v_cvt_pk_bf16_f32 v103, v108, v109
	global_store_dwordx4 v[118:119], v[100:103], off offset:256
	ds_read_b32 v100, v168 offset:128
	s_nop 0
	v_or_b32_e32 v101, 32, v163
	v_mad_i64_i32 v[102:103], s[6:7], v101, s65, v[150:151]
	v_lshl_add_u64 v[102:103], v[102:103], 0, v[152:153]
	s_waitcnt lgkmcnt(0)
	v_pk_mul_f32 v[98:99], v[98:99], v[100:101] op_sel_hi:[1,0]
	v_pk_mul_f32 v[96:97], v[96:97], v[100:101] op_sel_hi:[1,0]
	v_pk_mul_f32 v[104:105], v[94:95], v[100:101] op_sel_hi:[1,0]
	v_pk_mul_f32 v[94:95], v[92:93], v[100:101] op_sel_hi:[1,0]
	v_cvt_pk_bf16_f32 v92, v96, v97
	v_cvt_pk_bf16_f32 v93, v98, v99
	v_pk_mul_f32 v[88:89], v[88:89], v[100:101] op_sel_hi:[1,0]
	v_cvt_pk_bf16_f32 v94, v94, v95
	v_cvt_pk_bf16_f32 v95, v104, v105
	global_store_dwordx4 v[102:103], v[92:95], off
	v_pk_mul_f32 v[90:91], v[90:91], v[100:101] op_sel_hi:[1,0]
	s_nop 0
	v_pk_mul_f32 v[92:93], v[86:87], v[100:101] op_sel_hi:[1,0]
	v_pk_mul_f32 v[86:87], v[84:85], v[100:101] op_sel_hi:[1,0]
	v_cvt_pk_bf16_f32 v84, v88, v89
	v_cvt_pk_bf16_f32 v85, v90, v91
	s_nop 0
	v_cvt_pk_bf16_f32 v86, v86, v87
	v_cvt_pk_bf16_f32 v87, v92, v93
	global_store_dwordx4 v[102:103], v[84:87], off offset:256
	ds_read_b32 v84, v168 offset:192
	s_nop 0
	v_or_b32_e32 v85, 48, v163
	v_mad_i64_i32 v[86:87], s[6:7], v85, s65, v[150:151]
	v_lshl_add_u64 v[86:87], v[86:87], 0, v[152:153]
	s_waitcnt lgkmcnt(0)
	v_pk_mul_f32 v[82:83], v[82:83], v[84:85] op_sel_hi:[1,0]
	v_pk_mul_f32 v[80:81], v[80:81], v[84:85] op_sel_hi:[1,0]
	v_pk_mul_f32 v[88:89], v[78:79], v[84:85] op_sel_hi:[1,0]
	v_pk_mul_f32 v[78:79], v[76:77], v[84:85] op_sel_hi:[1,0]
	v_cvt_pk_bf16_f32 v76, v80, v81
	v_cvt_pk_bf16_f32 v77, v82, v83
	v_pk_mul_f32 v[72:73], v[72:73], v[84:85] op_sel_hi:[1,0]
	v_cvt_pk_bf16_f32 v78, v78, v79
	v_cvt_pk_bf16_f32 v79, v88, v89
	global_store_dwordx4 v[86:87], v[76:79], off
	v_pk_mul_f32 v[74:75], v[74:75], v[84:85] op_sel_hi:[1,0]
	s_nop 0
	v_pk_mul_f32 v[76:77], v[70:71], v[84:85] op_sel_hi:[1,0]
	v_pk_mul_f32 v[70:71], v[68:69], v[84:85] op_sel_hi:[1,0]
	v_cvt_pk_bf16_f32 v68, v72, v73
	v_cvt_pk_bf16_f32 v69, v74, v75
	s_nop 0
	v_cvt_pk_bf16_f32 v70, v70, v71
	v_cvt_pk_bf16_f32 v71, v76, v77
	global_store_dwordx4 v[86:87], v[68:71], off offset:256
	ds_read_b32 v68, v168 offset:512
	s_nop 0
	v_add_u32_e32 v69, 0x80, v163
	v_mad_i64_i32 v[70:71], s[6:7], v69, s65, v[150:151]
	v_lshl_add_u64 v[70:71], v[70:71], 0, v[152:153]
	s_waitcnt lgkmcnt(0)
	v_pk_mul_f32 v[66:67], v[66:67], v[68:69] op_sel_hi:[1,0]
	v_pk_mul_f32 v[64:65], v[64:65], v[68:69] op_sel_hi:[1,0]
	v_pk_mul_f32 v[72:73], v[62:63], v[68:69] op_sel_hi:[1,0]
	v_pk_mul_f32 v[62:63], v[60:61], v[68:69] op_sel_hi:[1,0]
	v_cvt_pk_bf16_f32 v60, v64, v65
	v_cvt_pk_bf16_f32 v61, v66, v67
	v_pk_mul_f32 v[56:57], v[56:57], v[68:69] op_sel_hi:[1,0]
	v_cvt_pk_bf16_f32 v62, v62, v63
	v_cvt_pk_bf16_f32 v63, v72, v73
	global_store_dwordx4 v[70:71], v[60:63], off
	v_pk_mul_f32 v[58:59], v[58:59], v[68:69] op_sel_hi:[1,0]
	s_nop 0
	v_pk_mul_f32 v[60:61], v[54:55], v[68:69] op_sel_hi:[1,0]
	v_pk_mul_f32 v[54:55], v[52:53], v[68:69] op_sel_hi:[1,0]
	v_cvt_pk_bf16_f32 v52, v56, v57
	v_cvt_pk_bf16_f32 v53, v58, v59
	s_nop 0
	v_cvt_pk_bf16_f32 v54, v54, v55
	v_cvt_pk_bf16_f32 v55, v60, v61
	global_store_dwordx4 v[70:71], v[52:55], off offset:256
	ds_read_b32 v52, v168 offset:576
	s_nop 0
	v_add_u32_e32 v53, 0x90, v163
	v_mad_i64_i32 v[54:55], s[6:7], v53, s65, v[150:151]
	v_lshl_add_u64 v[54:55], v[54:55], 0, v[152:153]
	s_waitcnt lgkmcnt(0)
	v_pk_mul_f32 v[50:51], v[50:51], v[52:53] op_sel_hi:[1,0]
	v_pk_mul_f32 v[48:49], v[48:49], v[52:53] op_sel_hi:[1,0]
	v_pk_mul_f32 v[56:57], v[46:47], v[52:53] op_sel_hi:[1,0]
	v_pk_mul_f32 v[46:47], v[44:45], v[52:53] op_sel_hi:[1,0]
	v_cvt_pk_bf16_f32 v44, v48, v49
	v_cvt_pk_bf16_f32 v45, v50, v51
	v_pk_mul_f32 v[40:41], v[40:41], v[52:53] op_sel_hi:[1,0]
	v_cvt_pk_bf16_f32 v46, v46, v47
	v_cvt_pk_bf16_f32 v47, v56, v57
	global_store_dwordx4 v[54:55], v[44:47], off
	v_pk_mul_f32 v[42:43], v[42:43], v[52:53] op_sel_hi:[1,0]
	s_nop 0
	v_pk_mul_f32 v[44:45], v[38:39], v[52:53] op_sel_hi:[1,0]
	v_pk_mul_f32 v[38:39], v[36:37], v[52:53] op_sel_hi:[1,0]
	v_cvt_pk_bf16_f32 v36, v40, v41
	v_cvt_pk_bf16_f32 v37, v42, v43
	s_nop 0
	v_cvt_pk_bf16_f32 v38, v38, v39
	v_cvt_pk_bf16_f32 v39, v44, v45
	global_store_dwordx4 v[54:55], v[36:39], off offset:256
	ds_read_b32 v36, v168 offset:640
	s_nop 0
	v_add_u32_e32 v37, 0xa0, v163
	v_mad_i64_i32 v[38:39], s[6:7], v37, s65, v[150:151]
	v_lshl_add_u64 v[38:39], v[38:39], 0, v[152:153]
	s_waitcnt lgkmcnt(0)
	v_pk_mul_f32 v[34:35], v[34:35], v[36:37] op_sel_hi:[1,0]
	v_pk_mul_f32 v[32:33], v[32:33], v[36:37] op_sel_hi:[1,0]
	v_pk_mul_f32 v[40:41], v[30:31], v[36:37] op_sel_hi:[1,0]
	v_pk_mul_f32 v[30:31], v[28:29], v[36:37] op_sel_hi:[1,0]
	v_cvt_pk_bf16_f32 v28, v32, v33
	v_cvt_pk_bf16_f32 v29, v34, v35
	v_pk_mul_f32 v[24:25], v[24:25], v[36:37] op_sel_hi:[1,0]
	v_cvt_pk_bf16_f32 v30, v30, v31
	v_cvt_pk_bf16_f32 v31, v40, v41
	global_store_dwordx4 v[38:39], v[28:31], off
	v_pk_mul_f32 v[26:27], v[26:27], v[36:37] op_sel_hi:[1,0]
	s_nop 0
	v_pk_mul_f32 v[28:29], v[22:23], v[36:37] op_sel_hi:[1,0]
	v_pk_mul_f32 v[22:23], v[20:21], v[36:37] op_sel_hi:[1,0]
	v_cvt_pk_bf16_f32 v20, v24, v25
	v_cvt_pk_bf16_f32 v21, v26, v27
	s_nop 0
	v_cvt_pk_bf16_f32 v22, v22, v23
	v_cvt_pk_bf16_f32 v23, v28, v29
	global_store_dwordx4 v[38:39], v[20:23], off offset:256
	ds_read_b32 v20, v168 offset:704
	s_nop 0
	v_add_u32_e32 v21, 0xb0, v163
	v_mad_i64_i32 v[22:23], s[6:7], v21, s65, v[150:151]
	v_lshl_add_u64 v[22:23], v[22:23], 0, v[152:153]
	s_waitcnt lgkmcnt(0)
	v_pk_mul_f32 v[18:19], v[18:19], v[20:21] op_sel_hi:[1,0]
	v_pk_mul_f32 v[16:17], v[16:17], v[20:21] op_sel_hi:[1,0]
	v_pk_mul_f32 v[24:25], v[14:15], v[20:21] op_sel_hi:[1,0]
	v_pk_mul_f32 v[14:15], v[12:13], v[20:21] op_sel_hi:[1,0]
	v_cvt_pk_bf16_f32 v12, v16, v17
	v_cvt_pk_bf16_f32 v13, v18, v19
	v_pk_mul_f32 v[10:11], v[10:11], v[20:21] op_sel_hi:[1,0]
	v_cvt_pk_bf16_f32 v14, v14, v15
	v_cvt_pk_bf16_f32 v15, v24, v25
	global_store_dwordx4 v[22:23], v[12:15], off
	v_pk_mul_f32 v[8:9], v[8:9], v[20:21] op_sel_hi:[1,0]
	s_nop 0
	v_pk_mul_f32 v[12:13], v[6:7], v[20:21] op_sel_hi:[1,0]
	v_pk_mul_f32 v[6:7], v[4:5], v[20:21] op_sel_hi:[1,0]
	v_cvt_pk_bf16_f32 v4, v8, v9
	v_cvt_pk_bf16_f32 v5, v10, v11
	s_nop 0
	v_cvt_pk_bf16_f32 v6, v6, v7
	v_cvt_pk_bf16_f32 v7, v12, v13
	global_store_dwordx4 v[22:23], v[4:7], off offset:256
	s_and_saveexec_b64 s[6:7], s[50:51]
	s_cbranch_execz .LBB0_436
	s_waitcnt vmcnt(16)
	v_ffbh_u32_e32 v226, v223
	v_min_u32_e32 v226, 32, v226
	v_lshlrev_b64 v[222:223], v226, v[222:223]
	v_min_u32_e32 v222, 1, v222
	v_or_b32_e32 v222, v223, v222
	v_cvt_f32_u32_e32 v222, v222
	v_sub_u32_e32 v223, 32, v226
	v_ldexp_f32 v222, v222, v223
	v_fmamk_f32 v222, v222, 0x2f800000, v159
	v_mul_f32_e32 v223, 0x4f800000, v222
	v_cmp_gt_f32_e32 vcc, s64, v222
	s_nop 1
	v_cndmask_b32_e32 v222, v222, v223, vcc
	v_sqrt_f32_e32 v223, v222
	s_nop 0
	v_add_u32_e32 v226, -1, v223
	v_add_u32_e32 v227, 1, v223
	v_fma_f32 v161, -v226, v223, v222
	v_fma_f32 v228, -v227, v223, v222
	v_cmp_ge_f32_e64 s[50:51], 0, v161
	s_nop 1
	v_cndmask_b32_e64 v223, v223, v226, s[50:51]
	v_cmp_lt_f32_e64 s[50:51], 0, v228
	s_nop 1
	v_cndmask_b32_e64 v223, v223, v227, s[50:51]
	v_mul_f32_e32 v226, 0x37800000, v223
	v_cndmask_b32_e32 v223, v223, v226, vcc
	v_cmp_class_f32_e32 vcc, v222, v160
	s_nop 1
	v_cndmask_b32_e32 v161, v223, v222, vcc
	v_div_scale_f32 v4, s[50:51], v161, v161, 1.0
	v_rcp_f32_e32 v5, v4
	v_div_scale_f32 v6, vcc, 1.0, v161, 1.0
	s_lshl_b32 s0, s57, 10
	v_fma_f32 v7, -v4, v5, 1.0
	v_fmac_f32_e32 v5, v7, v5
	v_mul_f32_e32 v7, v6, v5
	v_fma_f32 v8, -v4, v7, v6
	v_fmac_f32_e32 v7, v8, v5
	v_fma_f32 v4, -v4, v7, v6
	v_div_fmas_f32 v4, v4, v5, v7
	s_xor_b32 s0, s0, 0x400
	v_div_fixup_f32 v4, v4, v161, 1.0
	v_add_u32_e32 v5, s0, v1
	ds_write_b32 v5, v4

.LBB0_1202:
	s_ashr_i32 s25, s24, 31
	s_lshl_b64 s[26:27], s[24:25], 21
	s_add_u32 s26, s1, s26
	s_addc_u32 s27, s19, s27
	s_and_b64 s[28:29], s[4:5], exec
	s_cselect_b32 s25, s27, s43
	s_cselect_b32 s31, s26, s42
	s_ashr_i32 s23, s22, 31
	s_lshl_b64 s[28:29], s[22:23], 21
	s_add_u32 s28, s35, s28
	s_addc_u32 s29, s45, s29
	s_and_b64 s[52:53], s[4:5], exec
	s_cselect_b32 s23, s29, s51
	s_cselect_b32 s62, s28, s50
	s_add_u32 s42, s42, 0x100080
	s_addc_u32 s43, s43, 0
	s_add_u32 s63, s50, 0x100
	v_mov_b32_e32 v4, 0
	s_addc_u32 s64, s51, 0
	s_mov_b32 s65, -2
	s_waitcnt lgkmcnt(0)
	v_mov_b32_e32 v5, 0
	v_mov_b64_e32 v[6:7], 0
	v_mov_b64_e32 v[8:9], 0
	v_mov_b64_e32 v[10:11], 0
	v_mov_b64_e32 v[20:21], 0
	v_mov_b64_e32 v[22:23], 0
	v_mov_b64_e32 v[24:25], 0
	v_mov_b64_e32 v[26:27], 0
	v_mov_b64_e32 v[36:37], 0
	v_mov_b64_e32 v[38:39], 0
	v_mov_b64_e32 v[40:41], 0
	v_mov_b64_e32 v[42:43], 0
	v_mov_b64_e32 v[52:53], 0
	v_mov_b64_e32 v[54:55], 0
	v_mov_b64_e32 v[56:57], 0
	v_mov_b64_e32 v[58:59], 0
	v_mov_b64_e32 v[12:13], 0
	v_mov_b64_e32 v[14:15], 0
	v_mov_b64_e32 v[16:17], 0
	v_mov_b64_e32 v[18:19], 0
	v_mov_b64_e32 v[28:29], 0
	v_mov_b64_e32 v[30:31], 0
	v_mov_b64_e32 v[32:33], 0
	v_mov_b64_e32 v[34:35], 0
	v_mov_b64_e32 v[44:45], 0
	v_mov_b64_e32 v[46:47], 0
	v_mov_b64_e32 v[48:49], 0
	v_mov_b64_e32 v[50:51], 0
	v_mov_b64_e32 v[60:61], 0
	v_mov_b64_e32 v[62:63], 0
	v_mov_b64_e32 v[64:65], 0
	v_mov_b64_e32 v[66:67], 0
	v_mov_b64_e32 v[68:69], 0
	v_mov_b64_e32 v[70:71], 0
	v_mov_b64_e32 v[72:73], 0
	v_mov_b64_e32 v[74:75], 0
	v_mov_b64_e32 v[84:85], 0
	v_mov_b64_e32 v[86:87], 0
	v_mov_b64_e32 v[88:89], 0
	v_mov_b64_e32 v[90:91], 0
	v_mov_b64_e32 v[100:101], 0
	v_mov_b64_e32 v[102:103], 0
	v_mov_b64_e32 v[104:105], 0
	v_mov_b64_e32 v[106:107], 0
	v_mov_b64_e32 v[116:117], 0
	v_mov_b64_e32 v[118:119], 0
	v_mov_b64_e32 v[120:121], 0
	v_mov_b64_e32 v[122:123], 0
	v_mov_b64_e32 v[76:77], 0
	v_mov_b64_e32 v[78:79], 0
	v_mov_b64_e32 v[80:81], 0
	v_mov_b64_e32 v[82:83], 0
	v_mov_b64_e32 v[92:93], 0
	v_mov_b64_e32 v[94:95], 0
	v_mov_b64_e32 v[96:97], 0
	v_mov_b64_e32 v[98:99], 0
	v_mov_b64_e32 v[108:109], 0
	v_mov_b64_e32 v[110:111], 0
	v_mov_b64_e32 v[112:113], 0
	v_mov_b64_e32 v[114:115], 0
	v_mov_b64_e32 v[124:125], 0
	v_mov_b64_e32 v[126:127], 0
	v_mov_b64_e32 v[128:129], 0
	v_mov_b64_e32 v[130:131], 0

.LBB0_1287:
	s_add_u32 s42, s42, 0x100080
	s_addc_u32 s43, s43, 0
	s_add_u32 s31, s50, 0x100
	v_mov_b32_e32 v4, 0
	s_addc_u32 s41, s51, 0
	s_mov_b32 s70, -2
	v_mov_b32_e32 v5, 0
	v_mov_b64_e32 v[6:7], 0
	v_mov_b64_e32 v[8:9], 0
	v_mov_b64_e32 v[10:11], 0
	v_mov_b64_e32 v[12:13], 0
	v_mov_b64_e32 v[14:15], 0
	v_mov_b64_e32 v[16:17], 0
	v_mov_b64_e32 v[18:19], 0
	v_mov_b64_e32 v[28:29], 0
	v_mov_b64_e32 v[30:31], 0
	v_mov_b64_e32 v[32:33], 0
	v_mov_b64_e32 v[34:35], 0
	v_mov_b64_e32 v[44:45], 0
	v_mov_b64_e32 v[46:47], 0
	v_mov_b64_e32 v[48:49], 0
	v_mov_b64_e32 v[50:51], 0
	v_mov_b64_e32 v[20:21], 0
	v_mov_b64_e32 v[22:23], 0
	v_mov_b64_e32 v[24:25], 0
	v_mov_b64_e32 v[26:27], 0
	v_mov_b64_e32 v[36:37], 0
	v_mov_b64_e32 v[38:39], 0
	v_mov_b64_e32 v[40:41], 0
	v_mov_b64_e32 v[42:43], 0
	v_mov_b64_e32 v[52:53], 0
	v_mov_b64_e32 v[54:55], 0
	v_mov_b64_e32 v[56:57], 0
	v_mov_b64_e32 v[58:59], 0
	v_mov_b64_e32 v[60:61], 0
	v_mov_b64_e32 v[62:63], 0
	v_mov_b64_e32 v[64:65], 0
	v_mov_b64_e32 v[66:67], 0
	v_mov_b64_e32 v[68:69], 0
	v_mov_b64_e32 v[70:71], 0
	v_mov_b64_e32 v[72:73], 0
	v_mov_b64_e32 v[74:75], 0
	v_mov_b64_e32 v[76:77], 0
	v_mov_b64_e32 v[78:79], 0
	v_mov_b64_e32 v[80:81], 0
	v_mov_b64_e32 v[82:83], 0
	v_mov_b64_e32 v[92:93], 0
	v_mov_b64_e32 v[94:95], 0
	v_mov_b64_e32 v[96:97], 0
	v_mov_b64_e32 v[98:99], 0
	v_mov_b64_e32 v[108:109], 0
	v_mov_b64_e32 v[110:111], 0
	v_mov_b64_e32 v[112:113], 0
	v_mov_b64_e32 v[114:115], 0
	v_mov_b64_e32 v[84:85], 0
	v_mov_b64_e32 v[86:87], 0
	v_mov_b64_e32 v[88:89], 0
	v_mov_b64_e32 v[90:91], 0
	v_mov_b64_e32 v[100:101], 0
	v_mov_b64_e32 v[102:103], 0
	v_mov_b64_e32 v[104:105], 0
	v_mov_b64_e32 v[106:107], 0
	v_mov_b64_e32 v[116:117], 0
	v_mov_b64_e32 v[118:119], 0
	v_mov_b64_e32 v[120:121], 0
	v_mov_b64_e32 v[122:123], 0
	v_mov_b64_e32 v[124:125], 0
	v_mov_b64_e32 v[126:127], 0
	v_mov_b64_e32 v[128:129], 0
	v_mov_b64_e32 v[130:131], 0

.LBB0_1414:
	s_ashr_i32 s25, s24, 31
	s_lshl_b64 s[26:27], s[24:25], 18
	s_add_u32 s26, s1, s26
	s_addc_u32 s27, s18, s27
	s_and_b64 s[28:29], s[4:5], exec
	s_cselect_b32 s25, s27, s43
	s_cselect_b32 s31, s26, s42
	s_ashr_i32 s23, s22, 31
	s_lshl_b64 s[28:29], s[22:23], 18
	s_add_u32 s28, s19, s28
	s_addc_u32 s29, s35, s29
	s_and_b64 s[52:53], s[4:5], exec
	s_cselect_b32 s23, s29, s51
	s_cselect_b32 s61, s28, s50
	s_add_u32 s42, s42, 0x20080
	s_addc_u32 s43, s43, 0
	s_add_u32 s62, s50, 0x100
	v_mov_b32_e32 v4, 0
	s_addc_u32 s63, s51, 0
	s_mov_b32 s64, -2
	s_waitcnt lgkmcnt(0)
	v_mov_b32_e32 v5, 0
	v_mov_b64_e32 v[6:7], 0
	v_mov_b64_e32 v[8:9], 0
	v_mov_b64_e32 v[10:11], 0
	v_mov_b64_e32 v[20:21], 0
	v_mov_b64_e32 v[22:23], 0
	v_mov_b64_e32 v[24:25], 0
	v_mov_b64_e32 v[26:27], 0
	v_mov_b64_e32 v[36:37], 0
	v_mov_b64_e32 v[38:39], 0
	v_mov_b64_e32 v[40:41], 0
	v_mov_b64_e32 v[42:43], 0
	v_mov_b64_e32 v[52:53], 0
	v_mov_b64_e32 v[54:55], 0
	v_mov_b64_e32 v[56:57], 0
	v_mov_b64_e32 v[58:59], 0
	v_mov_b64_e32 v[12:13], 0
	v_mov_b64_e32 v[14:15], 0
	v_mov_b64_e32 v[16:17], 0
	v_mov_b64_e32 v[18:19], 0
	v_mov_b64_e32 v[28:29], 0
	v_mov_b64_e32 v[30:31], 0
	v_mov_b64_e32 v[32:33], 0
	v_mov_b64_e32 v[34:35], 0
	v_mov_b64_e32 v[44:45], 0
	v_mov_b64_e32 v[46:47], 0
	v_mov_b64_e32 v[48:49], 0
	v_mov_b64_e32 v[50:51], 0
	v_mov_b64_e32 v[60:61], 0
	v_mov_b64_e32 v[62:63], 0
	v_mov_b64_e32 v[64:65], 0
	v_mov_b64_e32 v[66:67], 0
	v_mov_b64_e32 v[68:69], 0
	v_mov_b64_e32 v[70:71], 0
	v_mov_b64_e32 v[72:73], 0
	v_mov_b64_e32 v[74:75], 0
	v_mov_b64_e32 v[84:85], 0
	v_mov_b64_e32 v[86:87], 0
	v_mov_b64_e32 v[88:89], 0
	v_mov_b64_e32 v[90:91], 0
	v_mov_b64_e32 v[100:101], 0
	v_mov_b64_e32 v[102:103], 0
	v_mov_b64_e32 v[104:105], 0
	v_mov_b64_e32 v[106:107], 0
	v_mov_b64_e32 v[116:117], 0
	v_mov_b64_e32 v[118:119], 0
	v_mov_b64_e32 v[120:121], 0
	v_mov_b64_e32 v[122:123], 0
	v_mov_b64_e32 v[76:77], 0
	v_mov_b64_e32 v[78:79], 0
	v_mov_b64_e32 v[80:81], 0
	v_mov_b64_e32 v[82:83], 0
	v_mov_b64_e32 v[92:93], 0
	v_mov_b64_e32 v[94:95], 0
	v_mov_b64_e32 v[96:97], 0
	v_mov_b64_e32 v[98:99], 0
	v_mov_b64_e32 v[108:109], 0
	v_mov_b64_e32 v[110:111], 0
	v_mov_b64_e32 v[112:113], 0
	v_mov_b64_e32 v[114:115], 0
	v_mov_b64_e32 v[124:125], 0
	v_mov_b64_e32 v[126:127], 0
	v_mov_b64_e32 v[128:129], 0
	v_mov_b64_e32 v[130:131], 0

.LBB0_1502:
	s_ashr_i32 s31, s30, 31
	s_lshl_b64 s[40:41], s[30:31], 21
	s_add_u32 s40, s19, s40
	s_addc_u32 s41, s35, s41
	s_and_b64 s[42:43], exec, s[6:7]
	s_cselect_b32 s31, s55, s41
	s_cselect_b32 s71, s54, s40
	s_ashr_i32 s29, s28, 31
	s_lshl_b64 s[42:43], s[28:29], 21
	s_add_u32 s42, s45, s42
	s_addc_u32 s43, s46, s43
	s_and_b64 s[58:59], exec, s[6:7]
	s_cselect_b32 s29, s57, s43
	s_cselect_b32 s72, s56, s42
	s_add_u32 s54, s54, 0x100080
	s_addc_u32 s55, s55, 0
	s_add_u32 s73, s56, 0x100
	v_mov_b32_e32 v8, 0
	s_addc_u32 s74, s57, 0
	s_mov_b32 s75, -2
	v_mov_b32_e32 v9, 0
	v_mov_b64_e32 v[10:11], 0
	v_mov_b64_e32 v[12:13], 0
	v_mov_b64_e32 v[14:15], 0
	v_mov_b64_e32 v[24:25], 0
	v_mov_b64_e32 v[26:27], 0
	v_mov_b64_e32 v[28:29], 0
	v_mov_b64_e32 v[30:31], 0
	v_mov_b64_e32 v[40:41], 0
	v_mov_b64_e32 v[42:43], 0
	v_mov_b64_e32 v[44:45], 0
	v_mov_b64_e32 v[46:47], 0
	v_mov_b64_e32 v[56:57], 0
	v_mov_b64_e32 v[58:59], 0
	v_mov_b64_e32 v[60:61], 0
	v_mov_b64_e32 v[62:63], 0
	v_mov_b64_e32 v[16:17], 0
	v_mov_b64_e32 v[18:19], 0
	v_mov_b64_e32 v[20:21], 0
	v_mov_b64_e32 v[22:23], 0
	v_mov_b64_e32 v[32:33], 0
	v_mov_b64_e32 v[34:35], 0
	v_mov_b64_e32 v[36:37], 0
	v_mov_b64_e32 v[38:39], 0
	v_mov_b64_e32 v[48:49], 0
	v_mov_b64_e32 v[50:51], 0
	v_mov_b64_e32 v[52:53], 0
	v_mov_b64_e32 v[54:55], 0
	v_mov_b64_e32 v[64:65], 0
	v_mov_b64_e32 v[66:67], 0
	v_mov_b64_e32 v[68:69], 0
	v_mov_b64_e32 v[70:71], 0
	v_mov_b64_e32 v[72:73], 0
	v_mov_b64_e32 v[74:75], 0
	v_mov_b64_e32 v[76:77], 0
	v_mov_b64_e32 v[78:79], 0
	v_mov_b64_e32 v[88:89], 0
	v_mov_b64_e32 v[90:91], 0
	v_mov_b64_e32 v[92:93], 0
	v_mov_b64_e32 v[94:95], 0
	v_mov_b64_e32 v[104:105], 0
	v_mov_b64_e32 v[106:107], 0
	v_mov_b64_e32 v[108:109], 0
	v_mov_b64_e32 v[110:111], 0
	v_mov_b64_e32 v[120:121], 0
	v_mov_b64_e32 v[122:123], 0
	v_mov_b64_e32 v[124:125], 0
	v_mov_b64_e32 v[126:127], 0
	v_mov_b64_e32 v[80:81], 0
	v_mov_b64_e32 v[82:83], 0
	v_mov_b64_e32 v[84:85], 0
	v_mov_b64_e32 v[86:87], 0
	v_mov_b64_e32 v[96:97], 0
	v_mov_b64_e32 v[98:99], 0
	v_mov_b64_e32 v[100:101], 0
	v_mov_b64_e32 v[102:103], 0
	v_mov_b64_e32 v[112:113], 0
	v_mov_b64_e32 v[114:115], 0
	v_mov_b64_e32 v[116:117], 0
	v_mov_b64_e32 v[118:119], 0
	v_mov_b64_e32 v[128:129], 0
	v_mov_b64_e32 v[130:131], 0
	v_mov_b64_e32 v[136:137], 0
	v_mov_b64_e32 v[138:139], 0

.LBB0_1506:
	s_nor_b64 s[54:55], s[2:3], s[6:7]
	v_mov_b32_e32 v164, 0x3a83126f
	s_and_saveexec_b64 s[56:57], s[54:55]
	s_cbranch_execz .LBB0_1508
	v_lshl_or_b32 v226, s30, 8, v0
	v_ashrrev_i32_e32 v227, 31, v226
	v_lshl_add_u64 v[226:227], v[226:227], 3, s[8:9]
	global_load_dwordx2 v[224:225], v[226:227], off
.LBB0_1508:
	s_or_b64 exec, exec, s[56:57]
	v_lshl_add_u32 v165, s60, 10, v157
	ds_read_b32 v171, v165
	v_pk_mul_f32 v[126:127], v[138:139], v[126:127]
	v_pk_mul_f32 v[122:123], v[130:131], v[122:123]
	v_pk_mul_f32 v[120:121], v[128:129], v[120:121]
	v_pk_mul_f32 v[110:111], v[118:119], v[110:111]
	s_waitcnt lgkmcnt(0)
	v_mul_f32_e32 v170, 0xbfb8aa3b, v171
	v_pk_mul_f32 v[132:133], v[138:139], v[170:171] op_sel_hi:[1,0]
	v_pk_mul_f32 v[134:135], v[136:137], v[170:171] op_sel_hi:[1,0]
	v_exp_f32_e32 v168, v132
	v_exp_f32_e32 v166, v134
	v_exp_f32_e32 v167, v135
	v_exp_f32_e32 v169, v133
	v_mov_b64_e32 v[134:135], v[6:7]
	v_mul_f32_e32 v174, v171, v171
	v_pk_mul_f32 v[172:173], v[130:131], v[170:171] op_sel_hi:[1,0]
	v_pk_mul_f32 v[170:171], v[128:129], v[170:171] op_sel_hi:[1,0]
	v_mov_b64_e32 v[132:133], v[4:5]
	v_exp_f32_e32 v170, v170
	v_exp_f32_e32 v171, v171
	v_exp_f32_e32 v172, v172
	v_exp_f32_e32 v173, v173
	v_pk_mul_f32 v[136:137], v[136:137], v[124:125]
	v_pk_mul_f32 v[138:139], v[126:127], v[174:175] op_sel_hi:[1,0]
	v_pk_add_f32 v[168:169], v[168:169], v[134:135]
	v_pk_add_f32 v[126:127], v[134:135], v[172:173]
	v_pk_add_f32 v[124:125], v[132:133], v[170:171]
	v_pk_add_f32 v[166:167], v[166:167], v[132:133]
	v_rcp_f32_e32 v124, v124
	v_rcp_f32_e32 v125, v125
	v_rcp_f32_e32 v126, v126
	v_rcp_f32_e32 v127, v127
	v_rcp_f32_e32 v166, v166
	v_rcp_f32_e32 v167, v167
	v_rcp_f32_e32 v168, v168
	v_rcp_f32_e32 v169, v169
	v_pk_mul_f32 v[136:137], v[136:137], v[174:175] op_sel_hi:[1,0]
	v_pk_mul_f32 v[122:123], v[122:123], v[174:175] op_sel_hi:[1,0]
	v_pk_mul_f32 v[120:121], v[120:121], v[174:175] op_sel_hi:[1,0]
	v_pk_mul_f32 v[122:123], v[122:123], v[126:127]
	v_pk_mul_f32 v[138:139], v[168:169], v[138:139]
	v_pk_mul_f32 v[136:137], v[166:167], v[136:137]
	v_pk_mul_f32 v[120:121], v[120:121], v[124:125]
	v_cvt_pk_bf16_f32 v126, v136, v137
	v_cvt_pk_bf16_f32 v127, v138, v139
	v_lshl_add_u32 v124, s50, 8, v3
	v_cvt_pk_bf16_f32 v128, v120, v121
	v_cvt_pk_bf16_f32 v129, v122, v123
	ds_read_b32 v125, v165 offset:64
	v_lshl_or_b32 v122, s52, 7, v158
	v_ashrrev_i32_e32 v123, 31, v122
	v_mov_b64_e32 v[120:121], s[22:23]
	v_mad_i64_i32 v[166:167], s[6:7], v124, s68, v[120:121]
	v_lshlrev_b64 v[122:123], 1, v[122:123]
	s_waitcnt lgkmcnt(0)
	v_mul_f32_e32 v130, 0xbfb8aa3b, v125
	v_lshl_add_u64 v[166:167], v[166:167], 0, v[122:123]
	global_store_dwordx4 v[166:167], v[126:129], off
	v_pk_mul_f32 v[138:139], v[118:119], v[130:131] op_sel_hi:[1,0]
	v_pk_mul_f32 v[136:137], v[116:117], v[130:131] op_sel_hi:[1,0]
	v_pk_mul_f32 v[128:129], v[114:115], v[130:131] op_sel_hi:[1,0]
	v_pk_mul_f32 v[126:127], v[112:113], v[130:131] op_sel_hi:[1,0]
	v_mul_f32_e32 v166, v125, v125
	v_exp_f32_e32 v126, v126
	v_exp_f32_e32 v127, v127
	v_exp_f32_e32 v128, v128
	v_exp_f32_e32 v129, v129
	v_exp_f32_e32 v136, v136
	v_exp_f32_e32 v137, v137
	v_exp_f32_e32 v138, v138
	v_exp_f32_e32 v139, v139
	v_pk_mul_f32 v[116:117], v[116:117], v[108:109]
	v_pk_mul_f32 v[118:119], v[110:111], v[166:167] op_sel_hi:[1,0]
	v_pk_mul_f32 v[106:107], v[114:115], v[106:107]
	v_pk_add_f32 v[110:111], v[134:135], v[128:129]
	v_pk_add_f32 v[108:109], v[132:133], v[126:127]
	v_rcp_f32_e32 v110, v110
	v_rcp_f32_e32 v108, v108
	v_rcp_f32_e32 v109, v109
	v_rcp_f32_e32 v111, v111
	v_pk_mul_f32 v[104:105], v[112:113], v[104:105]
	v_pk_add_f32 v[138:139], v[134:135], v[138:139]
	v_pk_add_f32 v[136:137], v[132:133], v[136:137]
	v_pk_mul_f32 v[106:107], v[106:107], v[166:167] op_sel_hi:[1,0]
	v_pk_mul_f32 v[104:105], v[104:105], v[166:167] op_sel_hi:[1,0]
	v_rcp_f32_e32 v136, v136
	v_rcp_f32_e32 v137, v137
	v_rcp_f32_e32 v138, v138
	v_rcp_f32_e32 v139, v139
	v_pk_mul_f32 v[116:117], v[116:117], v[166:167] op_sel_hi:[1,0]
	v_pk_mul_f32 v[110:111], v[106:107], v[110:111]
	v_pk_mul_f32 v[106:107], v[104:105], v[108:109]
	v_or_b32_e32 v114, 16, v124
	v_pk_mul_f32 v[118:119], v[138:139], v[118:119]
	v_pk_mul_f32 v[116:117], v[136:137], v[116:117]
	v_mad_i64_i32 v[114:115], s[6:7], v114, s68, v[120:121]
	v_cvt_pk_bf16_f32 v104, v116, v117
	v_cvt_pk_bf16_f32 v105, v118, v119
	v_cvt_pk_bf16_f32 v106, v106, v107
	v_cvt_pk_bf16_f32 v107, v110, v111
	ds_read_b32 v113, v165 offset:128
	v_lshl_add_u64 v[114:115], v[114:115], 0, v[122:123]
	global_store_dwordx4 v[114:115], v[104:107], off
	v_pk_mul_f32 v[94:95], v[102:103], v[94:95]
	v_pk_mul_f32 v[90:91], v[98:99], v[90:91]
	s_waitcnt lgkmcnt(0)
	v_mul_f32_e32 v112, 0xbfb8aa3b, v113
	v_pk_mul_f32 v[106:107], v[98:99], v[112:113] op_sel_hi:[1,0]
	v_pk_mul_f32 v[104:105], v[96:97], v[112:113] op_sel_hi:[1,0]
	v_pk_mul_f32 v[110:111], v[102:103], v[112:113] op_sel_hi:[1,0]
	v_pk_mul_f32 v[108:109], v[100:101], v[112:113] op_sel_hi:[1,0]
	v_mul_f32_e32 v114, v113, v113
	v_exp_f32_e32 v104, v104
	v_exp_f32_e32 v105, v105
	v_exp_f32_e32 v106, v106
	v_exp_f32_e32 v107, v107
	v_exp_f32_e32 v108, v108
	v_exp_f32_e32 v109, v109
	v_exp_f32_e32 v110, v110
	v_exp_f32_e32 v111, v111
	v_pk_mul_f32 v[100:101], v[100:101], v[92:93]
	v_pk_mul_f32 v[102:103], v[94:95], v[114:115] op_sel_hi:[1,0]
	v_pk_mul_f32 v[88:89], v[96:97], v[88:89]
	v_pk_add_f32 v[94:95], v[134:135], v[106:107]
	v_pk_add_f32 v[92:93], v[132:133], v[104:105]
	v_rcp_f32_e32 v94, v94
	v_rcp_f32_e32 v92, v92
	v_rcp_f32_e32 v93, v93
	v_rcp_f32_e32 v95, v95
	v_pk_add_f32 v[110:111], v[134:135], v[110:111]
	v_pk_add_f32 v[108:109], v[132:133], v[108:109]
	v_pk_mul_f32 v[90:91], v[90:91], v[114:115] op_sel_hi:[1,0]
	v_pk_mul_f32 v[88:89], v[88:89], v[114:115] op_sel_hi:[1,0]
	v_rcp_f32_e32 v108, v108
	v_rcp_f32_e32 v109, v109
	v_rcp_f32_e32 v110, v110
	v_rcp_f32_e32 v111, v111
	v_pk_mul_f32 v[100:101], v[100:101], v[114:115] op_sel_hi:[1,0]
	v_pk_mul_f32 v[94:95], v[90:91], v[94:95]
	v_pk_mul_f32 v[90:91], v[88:89], v[92:93]
	v_or_b32_e32 v98, 32, v124
	v_pk_mul_f32 v[102:103], v[110:111], v[102:103]
	v_pk_mul_f32 v[100:101], v[108:109], v[100:101]
	v_mad_i64_i32 v[98:99], s[6:7], v98, s68, v[120:121]
	v_cvt_pk_bf16_f32 v88, v100, v101
	v_cvt_pk_bf16_f32 v89, v102, v103
	v_cvt_pk_bf16_f32 v90, v90, v91
	v_cvt_pk_bf16_f32 v91, v94, v95
	ds_read_b32 v97, v165 offset:192
	v_lshl_add_u64 v[98:99], v[98:99], 0, v[122:123]
	global_store_dwordx4 v[98:99], v[88:91], off
	v_pk_mul_f32 v[78:79], v[86:87], v[78:79]
	v_pk_mul_f32 v[74:75], v[82:83], v[74:75]
	s_waitcnt lgkmcnt(0)
	v_mul_f32_e32 v96, 0xbfb8aa3b, v97
	v_pk_mul_f32 v[90:91], v[82:83], v[96:97] op_sel_hi:[1,0]
	v_pk_mul_f32 v[88:89], v[80:81], v[96:97] op_sel_hi:[1,0]
	v_pk_mul_f32 v[94:95], v[86:87], v[96:97] op_sel_hi:[1,0]
	v_pk_mul_f32 v[92:93], v[84:85], v[96:97] op_sel_hi:[1,0]
	v_mul_f32_e32 v98, v97, v97
	v_exp_f32_e32 v88, v88
	v_exp_f32_e32 v89, v89
	v_exp_f32_e32 v90, v90
	v_exp_f32_e32 v91, v91
	v_exp_f32_e32 v92, v92
	v_exp_f32_e32 v93, v93
	v_exp_f32_e32 v94, v94
	v_exp_f32_e32 v95, v95
	v_pk_mul_f32 v[84:85], v[84:85], v[76:77]
	v_pk_mul_f32 v[86:87], v[78:79], v[98:99] op_sel_hi:[1,0]
	v_pk_mul_f32 v[72:73], v[80:81], v[72:73]
	v_pk_add_f32 v[78:79], v[134:135], v[90:91]
	v_pk_add_f32 v[76:77], v[132:133], v[88:89]
	v_rcp_f32_e32 v78, v78
	v_rcp_f32_e32 v76, v76
	v_rcp_f32_e32 v77, v77
	v_rcp_f32_e32 v79, v79
	v_pk_add_f32 v[94:95], v[134:135], v[94:95]
	v_pk_add_f32 v[92:93], v[132:133], v[92:93]
	v_pk_mul_f32 v[74:75], v[74:75], v[98:99] op_sel_hi:[1,0]
	v_pk_mul_f32 v[72:73], v[72:73], v[98:99] op_sel_hi:[1,0]
	v_rcp_f32_e32 v92, v92
	v_rcp_f32_e32 v93, v93
	v_rcp_f32_e32 v94, v94
	v_rcp_f32_e32 v95, v95
	v_pk_mul_f32 v[84:85], v[84:85], v[98:99] op_sel_hi:[1,0]
	v_pk_mul_f32 v[78:79], v[74:75], v[78:79]
	v_pk_mul_f32 v[74:75], v[72:73], v[76:77]
	v_or_b32_e32 v82, 48, v124
	v_pk_mul_f32 v[86:87], v[94:95], v[86:87]
	v_pk_mul_f32 v[84:85], v[92:93], v[84:85]
	v_mad_i64_i32 v[82:83], s[6:7], v82, s68, v[120:121]
	v_cvt_pk_bf16_f32 v72, v84, v85
	v_cvt_pk_bf16_f32 v73, v86, v87
	v_cvt_pk_bf16_f32 v74, v74, v75
	v_cvt_pk_bf16_f32 v75, v78, v79
	ds_read_b32 v81, v165 offset:512
	v_lshl_add_u64 v[82:83], v[82:83], 0, v[122:123]
	global_store_dwordx4 v[82:83], v[72:75], off
	v_pk_mul_f32 v[62:63], v[70:71], v[62:63]
	v_pk_mul_f32 v[58:59], v[66:67], v[58:59]
	s_waitcnt lgkmcnt(0)
	v_mul_f32_e32 v80, 0xbfb8aa3b, v81
	v_pk_mul_f32 v[74:75], v[66:67], v[80:81] op_sel_hi:[1,0]
	v_pk_mul_f32 v[72:73], v[64:65], v[80:81] op_sel_hi:[1,0]
	v_pk_mul_f32 v[78:79], v[70:71], v[80:81] op_sel_hi:[1,0]
	v_pk_mul_f32 v[76:77], v[68:69], v[80:81] op_sel_hi:[1,0]
	v_mul_f32_e32 v82, v81, v81
	v_exp_f32_e32 v72, v72
	v_exp_f32_e32 v73, v73
	v_exp_f32_e32 v74, v74
	v_exp_f32_e32 v75, v75
	v_exp_f32_e32 v76, v76
	v_exp_f32_e32 v77, v77
	v_exp_f32_e32 v78, v78
	v_exp_f32_e32 v79, v79
	v_pk_mul_f32 v[68:69], v[68:69], v[60:61]
	v_pk_mul_f32 v[70:71], v[62:63], v[82:83] op_sel_hi:[1,0]
	v_pk_mul_f32 v[56:57], v[64:65], v[56:57]
	v_pk_add_f32 v[62:63], v[134:135], v[74:75]
	v_pk_add_f32 v[60:61], v[132:133], v[72:73]
	v_rcp_f32_e32 v62, v62
	v_rcp_f32_e32 v60, v60
	v_rcp_f32_e32 v61, v61
	v_rcp_f32_e32 v63, v63
	v_pk_add_f32 v[78:79], v[134:135], v[78:79]
	v_pk_add_f32 v[76:77], v[132:133], v[76:77]
	v_pk_mul_f32 v[58:59], v[58:59], v[82:83] op_sel_hi:[1,0]
	v_pk_mul_f32 v[56:57], v[56:57], v[82:83] op_sel_hi:[1,0]
	v_rcp_f32_e32 v76, v76
	v_rcp_f32_e32 v77, v77
	v_rcp_f32_e32 v78, v78
	v_rcp_f32_e32 v79, v79
	v_pk_mul_f32 v[68:69], v[68:69], v[82:83] op_sel_hi:[1,0]
	v_pk_mul_f32 v[62:63], v[58:59], v[62:63]
	v_pk_mul_f32 v[58:59], v[56:57], v[60:61]
	v_add_u32_e32 v66, 0x80, v124
	v_pk_mul_f32 v[70:71], v[78:79], v[70:71]
	v_pk_mul_f32 v[68:69], v[76:77], v[68:69]
	v_mad_i64_i32 v[66:67], s[6:7], v66, s68, v[120:121]
	v_cvt_pk_bf16_f32 v56, v68, v69
	v_cvt_pk_bf16_f32 v57, v70, v71
	v_cvt_pk_bf16_f32 v58, v58, v59
	v_cvt_pk_bf16_f32 v59, v62, v63
	ds_read_b32 v65, v165 offset:576
	v_lshl_add_u64 v[66:67], v[66:67], 0, v[122:123]
	global_store_dwordx4 v[66:67], v[56:59], off
	v_pk_mul_f32 v[46:47], v[54:55], v[46:47]
	v_pk_mul_f32 v[42:43], v[50:51], v[42:43]
	s_waitcnt lgkmcnt(0)
	v_mul_f32_e32 v64, 0xbfb8aa3b, v65
	v_pk_mul_f32 v[58:59], v[50:51], v[64:65] op_sel_hi:[1,0]
	v_pk_mul_f32 v[56:57], v[48:49], v[64:65] op_sel_hi:[1,0]
	v_pk_mul_f32 v[62:63], v[54:55], v[64:65] op_sel_hi:[1,0]
	v_pk_mul_f32 v[60:61], v[52:53], v[64:65] op_sel_hi:[1,0]
	v_mul_f32_e32 v66, v65, v65
	v_exp_f32_e32 v56, v56
	v_exp_f32_e32 v57, v57
	v_exp_f32_e32 v58, v58
	v_exp_f32_e32 v59, v59
	v_exp_f32_e32 v60, v60
	v_exp_f32_e32 v61, v61
	v_exp_f32_e32 v62, v62
	v_exp_f32_e32 v63, v63
	v_pk_mul_f32 v[52:53], v[52:53], v[44:45]
	v_pk_mul_f32 v[54:55], v[46:47], v[66:67] op_sel_hi:[1,0]
	v_pk_mul_f32 v[40:41], v[48:49], v[40:41]
	v_pk_add_f32 v[46:47], v[134:135], v[58:59]
	v_pk_add_f32 v[44:45], v[132:133], v[56:57]
	v_rcp_f32_e32 v46, v46
	v_rcp_f32_e32 v44, v44
	v_rcp_f32_e32 v45, v45
	v_rcp_f32_e32 v47, v47
	v_pk_add_f32 v[62:63], v[134:135], v[62:63]
	v_pk_add_f32 v[60:61], v[132:133], v[60:61]
	v_pk_mul_f32 v[42:43], v[42:43], v[66:67] op_sel_hi:[1,0]
	v_pk_mul_f32 v[40:41], v[40:41], v[66:67] op_sel_hi:[1,0]
	v_rcp_f32_e32 v60, v60
	v_rcp_f32_e32 v61, v61
	v_rcp_f32_e32 v62, v62
	v_rcp_f32_e32 v63, v63
	v_pk_mul_f32 v[52:53], v[52:53], v[66:67] op_sel_hi:[1,0]
	v_pk_mul_f32 v[46:47], v[42:43], v[46:47]
	v_pk_mul_f32 v[42:43], v[40:41], v[44:45]
	v_add_u32_e32 v50, 0x90, v124
	v_pk_mul_f32 v[54:55], v[62:63], v[54:55]
	v_pk_mul_f32 v[52:53], v[60:61], v[52:53]
	v_mad_i64_i32 v[50:51], s[6:7], v50, s68, v[120:121]
	v_cvt_pk_bf16_f32 v40, v52, v53
	v_cvt_pk_bf16_f32 v41, v54, v55
	v_cvt_pk_bf16_f32 v42, v42, v43
	v_cvt_pk_bf16_f32 v43, v46, v47
	ds_read_b32 v49, v165 offset:640
	v_lshl_add_u64 v[50:51], v[50:51], 0, v[122:123]
	global_store_dwordx4 v[50:51], v[40:43], off
	v_pk_mul_f32 v[30:31], v[38:39], v[30:31]
	v_pk_mul_f32 v[26:27], v[34:35], v[26:27]
	s_waitcnt lgkmcnt(0)
	v_mul_f32_e32 v48, 0xbfb8aa3b, v49
	v_pk_mul_f32 v[42:43], v[34:35], v[48:49] op_sel_hi:[1,0]
	v_pk_mul_f32 v[40:41], v[32:33], v[48:49] op_sel_hi:[1,0]
	v_pk_mul_f32 v[46:47], v[38:39], v[48:49] op_sel_hi:[1,0]
	v_pk_mul_f32 v[44:45], v[36:37], v[48:49] op_sel_hi:[1,0]
	v_mul_f32_e32 v50, v49, v49
	v_exp_f32_e32 v40, v40
	v_exp_f32_e32 v41, v41
	v_exp_f32_e32 v42, v42
	v_exp_f32_e32 v43, v43
	v_exp_f32_e32 v44, v44
	v_exp_f32_e32 v45, v45
	v_exp_f32_e32 v46, v46
	v_exp_f32_e32 v47, v47
	v_pk_mul_f32 v[36:37], v[36:37], v[28:29]
	v_pk_mul_f32 v[38:39], v[30:31], v[50:51] op_sel_hi:[1,0]
	v_pk_mul_f32 v[24:25], v[32:33], v[24:25]
	v_pk_add_f32 v[30:31], v[134:135], v[42:43]
	v_pk_add_f32 v[28:29], v[132:133], v[40:41]
	v_rcp_f32_e32 v30, v30
	v_rcp_f32_e32 v28, v28
	v_rcp_f32_e32 v29, v29
	v_rcp_f32_e32 v31, v31
	v_pk_add_f32 v[46:47], v[134:135], v[46:47]
	v_pk_add_f32 v[44:45], v[132:133], v[44:45]
	v_pk_mul_f32 v[26:27], v[26:27], v[50:51] op_sel_hi:[1,0]
	v_pk_mul_f32 v[24:25], v[24:25], v[50:51] op_sel_hi:[1,0]
	v_rcp_f32_e32 v44, v44
	v_rcp_f32_e32 v45, v45
	v_rcp_f32_e32 v46, v46
	v_rcp_f32_e32 v47, v47
	v_pk_mul_f32 v[36:37], v[36:37], v[50:51] op_sel_hi:[1,0]
	v_pk_mul_f32 v[30:31], v[26:27], v[30:31]
	v_pk_mul_f32 v[26:27], v[24:25], v[28:29]
	v_add_u32_e32 v28, 0xa0, v124
	v_pk_mul_f32 v[38:39], v[46:47], v[38:39]
	v_pk_mul_f32 v[36:37], v[44:45], v[36:37]
	v_mad_i64_i32 v[32:33], s[6:7], v28, s68, v[120:121]
	v_cvt_pk_bf16_f32 v24, v36, v37
	v_cvt_pk_bf16_f32 v25, v38, v39
	v_cvt_pk_bf16_f32 v26, v26, v27
	v_cvt_pk_bf16_f32 v27, v30, v31
	ds_read_b32 v35, v165 offset:704
	v_lshl_add_u64 v[32:33], v[32:33], 0, v[122:123]
	global_store_dwordx4 v[32:33], v[24:27], off
	v_add_u32_e32 v32, 0xb0, v124
	v_pk_mul_f32 v[14:15], v[22:23], v[14:15]
	s_waitcnt lgkmcnt(0)
	v_mul_f32_e32 v34, 0xbfb8aa3b, v35
	v_pk_mul_f32 v[30:31], v[22:23], v[34:35] op_sel_hi:[1,0]
	v_pk_mul_f32 v[28:29], v[20:21], v[34:35] op_sel_hi:[1,0]
	v_exp_f32_e32 v30, v30
	v_exp_f32_e32 v28, v28
	v_exp_f32_e32 v29, v29
	v_exp_f32_e32 v31, v31
	v_mul_f32_e32 v36, v35, v35
	v_pk_add_f32 v[24:25], v[132:133], v[28:29]
	v_mad_i64_i32 v[28:29], s[6:7], v32, s68, v[120:121]
	v_pk_add_f32 v[26:27], v[134:135], v[30:31]
	v_lshl_add_u64 v[32:33], v[28:29], 0, v[122:123]
	v_pk_mul_f32 v[30:31], v[18:19], v[34:35] op_sel_hi:[1,0]
	v_pk_mul_f32 v[28:29], v[16:17], v[34:35] op_sel_hi:[1,0]
	v_exp_f32_e32 v30, v30
	v_exp_f32_e32 v28, v28
	v_exp_f32_e32 v29, v29
	v_exp_f32_e32 v31, v31
	v_pk_mul_f32 v[20:21], v[20:21], v[12:13]
	v_pk_mul_f32 v[22:23], v[14:15], v[36:37] op_sel_hi:[1,0]
	v_pk_mul_f32 v[10:11], v[18:19], v[10:11]
	v_pk_add_f32 v[14:15], v[134:135], v[30:31]
	v_pk_add_f32 v[12:13], v[132:133], v[28:29]
	v_rcp_f32_e32 v14, v14
	v_rcp_f32_e32 v12, v12
	v_rcp_f32_e32 v13, v13
	v_rcp_f32_e32 v15, v15
	v_pk_mul_f32 v[8:9], v[16:17], v[8:9]
	v_pk_mul_f32 v[10:11], v[10:11], v[36:37] op_sel_hi:[1,0]
	v_pk_mul_f32 v[8:9], v[8:9], v[36:37] op_sel_hi:[1,0]
	v_rcp_f32_e32 v24, v24
	v_rcp_f32_e32 v25, v25
	v_rcp_f32_e32 v26, v26
	v_rcp_f32_e32 v27, v27
	v_pk_mul_f32 v[20:21], v[20:21], v[36:37] op_sel_hi:[1,0]
	v_pk_mul_f32 v[14:15], v[10:11], v[14:15]
	v_pk_mul_f32 v[10:11], v[8:9], v[12:13]
	s_nop 0
	v_pk_mul_f32 v[22:23], v[26:27], v[22:23]
	v_pk_mul_f32 v[20:21], v[24:25], v[20:21]
	s_nop 0
	v_cvt_pk_bf16_f32 v8, v20, v21
	v_cvt_pk_bf16_f32 v9, v22, v23
	v_cvt_pk_bf16_f32 v10, v10, v11
	v_cvt_pk_bf16_f32 v11, v14, v15
	global_store_dwordx4 v[32:33], v[8:11], off
	s_and_saveexec_b64 s[6:7], s[54:55]
	s_cbranch_execz .LBB0_1510
	s_waitcnt vmcnt(8)
	v_ffbh_u32_e32 v226, v225
	v_min_u32_e32 v226, 32, v226
	v_lshlrev_b64 v[224:225], v226, v[224:225]
	v_min_u32_e32 v224, 1, v224
	v_or_b32_e32 v224, v225, v224
	v_cvt_f32_u32_e32 v224, v224
	v_sub_u32_e32 v225, 32, v226
	v_ldexp_f32 v224, v224, v225
	v_fmamk_f32 v224, v224, 0x2f800000, v162
	v_mul_f32_e32 v225, 0x4f800000, v224
	v_cmp_gt_f32_e32 vcc, s67, v224
	s_nop 1
	v_cndmask_b32_e32 v224, v224, v225, vcc
	v_sqrt_f32_e32 v225, v224
	s_nop 0
	v_add_u32_e32 v226, -1, v225
	v_add_u32_e32 v227, 1, v225
	v_fma_f32 v164, -v226, v225, v224
	v_fma_f32 v228, -v227, v225, v224
	v_cmp_ge_f32_e64 s[54:55], 0, v164
	s_nop 1
	v_cndmask_b32_e64 v225, v225, v226, s[54:55]
	v_cmp_lt_f32_e64 s[54:55], 0, v228
	s_nop 1
	v_cndmask_b32_e64 v225, v225, v227, s[54:55]
	v_mul_f32_e32 v226, 0x37800000, v225
	v_cndmask_b32_e32 v225, v225, v226, vcc
	v_cmp_class_f32_e32 vcc, v224, v163
	s_nop 1
	v_cndmask_b32_e32 v164, v225, v224, vcc
	v_div_scale_f32 v8, s[54:55], v164, v164, 1.0
	v_rcp_f32_e32 v9, v8
	v_div_scale_f32 v10, vcc, 1.0, v164, 1.0
	s_lshl_b32 s0, s60, 10
	v_fma_f32 v11, -v8, v9, 1.0
	v_fmac_f32_e32 v9, v11, v9
	v_mul_f32_e32 v11, v10, v9
	v_fma_f32 v12, -v8, v11, v10
	v_fmac_f32_e32 v11, v12, v9
	v_fma_f32 v8, -v8, v11, v10
	v_div_fmas_f32 v8, v8, v9, v11
	s_xor_b32 s0, s0, 0x400
	v_div_fixup_f32 v8, v8, v164, 1.0
	v_add_u32_e32 v9, s0, v1
	ds_write_b32 v9, v8

.LBB0_1671:
	s_add_u32 s30, s30, 0x2b0080
	s_addc_u32 s31, s31, 0
	s_add_u32 s64, s42, 0x100
	v_mov_b32_e32 v4, 0
	s_addc_u32 s65, s43, 0
	s_mov_b32 s66, -2
	s_waitcnt lgkmcnt(0)
	v_mov_b32_e32 v5, 0
	v_mov_b64_e32 v[6:7], 0
	v_mov_b64_e32 v[8:9], 0
	v_mov_b64_e32 v[10:11], 0
	v_mov_b64_e32 v[20:21], 0
	v_mov_b64_e32 v[22:23], 0
	v_mov_b64_e32 v[24:25], 0
	v_mov_b64_e32 v[26:27], 0
	v_mov_b64_e32 v[36:37], 0
	v_mov_b64_e32 v[38:39], 0
	v_mov_b64_e32 v[40:41], 0
	v_mov_b64_e32 v[42:43], 0
	v_mov_b64_e32 v[52:53], 0
	v_mov_b64_e32 v[54:55], 0
	v_mov_b64_e32 v[56:57], 0
	v_mov_b64_e32 v[58:59], 0
	v_mov_b64_e32 v[12:13], 0
	v_mov_b64_e32 v[14:15], 0
	v_mov_b64_e32 v[16:17], 0
	v_mov_b64_e32 v[18:19], 0
	v_mov_b64_e32 v[28:29], 0
	v_mov_b64_e32 v[30:31], 0
	v_mov_b64_e32 v[32:33], 0
	v_mov_b64_e32 v[34:35], 0
	v_mov_b64_e32 v[44:45], 0
	v_mov_b64_e32 v[46:47], 0
	v_mov_b64_e32 v[48:49], 0
	v_mov_b64_e32 v[50:51], 0
	v_mov_b64_e32 v[60:61], 0
	v_mov_b64_e32 v[62:63], 0
	v_mov_b64_e32 v[64:65], 0
	v_mov_b64_e32 v[66:67], 0
	v_mov_b64_e32 v[68:69], 0
	v_mov_b64_e32 v[70:71], 0
	v_mov_b64_e32 v[72:73], 0
	v_mov_b64_e32 v[74:75], 0
	v_mov_b64_e32 v[84:85], 0
	v_mov_b64_e32 v[86:87], 0
	v_mov_b64_e32 v[88:89], 0
	v_mov_b64_e32 v[90:91], 0
	v_mov_b64_e32 v[100:101], 0
	v_mov_b64_e32 v[102:103], 0
	v_mov_b64_e32 v[104:105], 0
	v_mov_b64_e32 v[106:107], 0
	v_mov_b64_e32 v[116:117], 0
	v_mov_b64_e32 v[118:119], 0
	v_mov_b64_e32 v[120:121], 0
	v_mov_b64_e32 v[122:123], 0
	v_mov_b64_e32 v[76:77], 0
	v_mov_b64_e32 v[78:79], 0
	v_mov_b64_e32 v[80:81], 0
	v_mov_b64_e32 v[82:83], 0
	v_mov_b64_e32 v[92:93], 0
	v_mov_b64_e32 v[94:95], 0
	v_mov_b64_e32 v[96:97], 0
	v_mov_b64_e32 v[98:99], 0
	v_mov_b64_e32 v[108:109], 0
	v_mov_b64_e32 v[110:111], 0
	v_mov_b64_e32 v[112:113], 0
	v_mov_b64_e32 v[114:115], 0
	v_mov_b64_e32 v[124:125], 0
	v_mov_b64_e32 v[126:127], 0
	v_mov_b64_e32 v[128:129], 0
	v_mov_b64_e32 v[130:131], 0
